# MLA unit start: wait before the first K/V stage loads leaves the previous unit's four output stores in flight
# speedup vs baseline: 1.0071x; 1.0071x over previous
.LBB0_520:
	v_readlane_b32 s13, v248, 13
	s_sub_i32 s4, s74, s13
	s_lshl_b32 s4, s4, 2
	v_readlane_b32 s6, v251, 2
	s_ashr_i32 s8, s74, 3
	s_add_i32 s4, s4, s23
	v_readlane_b32 s7, v251, 3
	s_and_b64 s[6:7], s[6:7], exec
	s_cselect_b32 s36, s4, s8
	s_ashr_i32 s6, s36, 4
	s_ashr_i32 s37, s36, 31
	s_ashr_i32 s7, s6, 31
	s_lshl_b64 s[8:9], s[36:37], 18
	s_add_u32 s14, s44, s8
	s_addc_u32 s15, s45, s9
	s_lshl_b64 s[10:11], s[6:7], 17
	s_add_u32 s18, s51, s10
	s_addc_u32 s19, s71, s11
	s_add_u32 s24, s2, s8
	s_addc_u32 s25, s3, s9
	s_ashr_i32 s38, s0, 7
	s_lshl_b32 s0, s38, 11
	s_lshl_b32 s12, s16, 11
	s_add_i32 s29, s0, 0
	s_and_b32 s0, s16, 1
	s_add_i32 s28, s12, 0
	s_lshl_b32 s12, s0, 10
	s_add_i32 s29, s29, s12
	s_lshl_b32 s12, s16, 10
	s_sub_i32 s37, s28, s12
	v_and_b32_e32 v0, 63, v4
	s_cmp_le_i32 s74, s13
	v_lshlrev_b32_e32 v102, 3, v0
	s_cbranch_scc0 .LBB0_522
	s_ashr_i32 s17, s16, 31
	s_lshl_b64 s[12:13], s[16:17], 15
	s_add_u32 s40, s14, s12
	s_addc_u32 s41, s15, s13
	s_ashr_i32 s39, s38, 31
	s_lshl_b64 s[12:13], s[38:39], 11
	s_lshl_b32 s30, s0, 6
	s_or_b32 s12, s12, s30
	v_or_b32_e32 v186, s12, v0
	s_lshl_b32 s12, s16, 4
	v_mov_b32_e32 v187, s13
	s_ashr_i32 s13, s12, 31
	s_lshl_b64 s[54:55], s[12:13], 6
	s_add_u32 s54, s24, s54
	v_lshlrev_b32_e32 v6, 4, v0
	v_mov_b32_e32 v7, v1
	s_addc_u32 s55, s25, s55
	s_add_i32 s13, s28, s75
	s_waitcnt vmcnt(4)
	v_lshl_add_u64 v[8:9], s[40:41], 0, v[6:7]
	s_mov_b32 m0, s13
	v_lshlrev_b64 v[2:3], 4, v[186:187]
	global_load_lds_dwordx4 v6, s[40:41]
	v_lshl_add_u64 v[14:15], v[8:9], 0, s[26:27]
	s_add_i32 m0, s13, 0x400
	s_add_i32 s13, s29, s75
	v_lshl_add_u64 v[10:11], s[18:19], 0, v[2:3]
	global_load_lds_dwordx4 v[14:15], off
	s_add_i32 m0, s13, 0x4000
	s_add_i32 s13, s37, s75
	global_load_lds_dwordx4 v[10:11], off
	s_add_i32 m0, s13, 0x6000
	v_lshl_add_u64 v[12:13], s[54:55], 0, v[6:7]
	global_load_lds_dwordx4 v6, s[54:55]
	s_add_i32 m0, s13, 0x8000
	s_add_i32 s13, s75, 0xa000
	s_cmp_lt_i32 s75, 0x14000
	v_lshl_add_u64 v[6:7], v[12:13], 0, s[48:49]
	s_cselect_b32 s13, s13, 0
	s_mov_b64 s[30:31], 0x800
	global_load_lds_dwordx4 v[6:7], off
	v_lshl_add_u64 v[6:7], v[8:9], 0, s[30:31]
	v_lshl_add_u64 v[10:11], v[10:11], 0, s[30:31]
	s_mov_b64 s[40:41], 0x2000
	s_add_i32 s30, s28, s13
	v_lshl_add_u64 v[14:15], v[12:13], 0, s[40:41]
	s_mov_b32 m0, s30
	s_mov_b64 s[40:41], 0xc00
	global_load_lds_dwordx4 v[6:7], off
	v_lshl_add_u64 v[6:7], v[8:9], 0, s[40:41]
	s_add_i32 m0, s30, 0x400
	s_add_i32 s30, s29, s13
	global_load_lds_dwordx4 v[6:7], off
	s_add_i32 m0, s30, 0x4000
	s_add_i32 s13, s37, s13
	global_load_lds_dwordx4 v[10:11], off
	s_add_i32 m0, s13, 0x6000
	s_mov_b64 s[40:41], 0x22000
	global_load_lds_dwordx4 v[14:15], off
	v_lshl_add_u64 v[6:7], v[12:13], 0, s[40:41]
	s_add_i32 m0, s13, 0x8000
	v_mov_b32_e32 v103, v1
	global_load_lds_dwordx4 v[6:7], off
	v_readfirstlane_b32 s13, v193
	s_nop 3
	s_lshr_b32 s13, s13, 8
	s_cmp_eq_u32 s13, 0
	s_cbranch_scc1 .Lmla_nox
	s_waitcnt vmcnt(5)
	s_barrier
